# mlstm stage A: state tile staged through per-wave LDS and stored with 2 dwordx4 instead of 16 two-byte stores (on v24)
# speedup vs baseline: 1.0045x; 1.0045x over previous
; __device__ __forceinline__ bf16_t f2bf(float f) { return (bf16_t)(cvt_pk_bf16(f, 0.f) & 0xffffu); }
; __device__ __forceinline__ bf16_t f2bf_sw(float f) { const unsigned u = __float_as_uint(f); return (bf16_t)((u + 0x7fffu + ((u >> 16) & 1u)) >> 16); }
; __device__ __forceinline__ void phase_mlstm_a(const Args& a, unsigned char* lds) {
;     ...
;         for (int i = tid; i < 1024; i += 512) { const int s = i >> 4, d0 = (i & 15) * 8; float f[8]; unpack8(*(const u32x4*)(P + (r0 + s) * LDP + C_MV + h * 128 + d0), f);
; #pragma unroll
;             for (int e = 0; e < 8; ++e) VT[(d0 + e) * 72 + s] = f2bf(f[e]); }
;         __syncthreads();
;         { const int s = tid >> 3, d0 = (tid & 7) * 8; float f[8]; unpack8(*(const u32x4*)(QK + (r0 + s) * 512 + 256 + h * 64 + d0), f); const float w = WS_[s];
; #pragma unroll
;             for (int e = 0; e < 8; ++e) KT[(d0 + e) * 72 + s] = f2bf(f[e] * w); }
;         __syncthreads();
;         bf16_t* st = ST + (size_t)item * 8192;
; #pragma unroll
;         for (int nt = 0; nt < 4; ++nt) {
;             const f32x4 acc = mma_lds(VT + wave * 16 * 72, 72, KT + nt * 16 * 72, 72, 64, lane);
; #pragma unroll
;             for (int j = 0; j < 4; ++j) st[(wave * 16 + (lane >> 4) * 4 + j) * 64 + nt * 16 + (lane & 15)] = f2bf_sw(acc[j]);
.LBB0_660:
	global_load_dwordx4 v[40:43], v[4:5], off
	v_and_b32_e32 v39, 0x78, v37
	v_mad_u32_u24 v39, v39, s26, v0
	v_add_co_u32_e32 v38, vcc, 0x200, v38
	s_xor_b64 s[20:21], vcc, -1
	s_and_b64 s[20:21], exec, s[20:21]
	v_add_u32_e32 v37, 0x1000, v37
	v_lshl_add_u64 v[4:5], v[4:5], 0, s[12:13]
	v_add_u32_e32 v0, 64, v0
	s_or_b64 s[18:19], s[20:21], s[18:19]
	s_waitcnt vmcnt(0)
	v_lshlrev_b32_e32 v44, 16, v40
	v_and_b32_e32 v40, 0xffff0000, v40
	v_cvt_pk_bf16_f32 v44, v44, v1
	ds_write_b16 v39, v44
	v_cvt_pk_bf16_f32 v40, v40, v1
	v_lshlrev_b32_e32 v45, 16, v41
	ds_write_b16 v39, v40 offset:144
	v_cvt_pk_bf16_f32 v40, v45, v1
	v_and_b32_e32 v41, 0xffff0000, v41
	ds_write_b16 v39, v40 offset:288
	v_cvt_pk_bf16_f32 v40, v41, v1
	v_lshlrev_b32_e32 v46, 16, v42
	ds_write_b16 v39, v40 offset:432
	v_cvt_pk_bf16_f32 v40, v46, v1
	v_and_b32_e32 v42, 0xffff0000, v42
	ds_write_b16 v39, v40 offset:576
	v_cvt_pk_bf16_f32 v40, v42, v1
	v_lshlrev_b32_e32 v47, 16, v43
	ds_write_b16 v39, v40 offset:720
	v_cvt_pk_bf16_f32 v40, v47, v1
	v_and_b32_e32 v43, 0xffff0000, v43
	ds_write_b16 v39, v40 offset:864
	v_cvt_pk_bf16_f32 v40, v43, v1
	ds_write_b16 v39, v40 offset:1008
	s_andn2_b64 exec, exec, s[18:19]
	s_cbranch_execnz .LBB0_660
	s_or_b64 exec, exec, s[18:19]
	v_lshl_add_u64 v[4:5], s[16:17], 0, v[128:129]
	v_lshlrev_b64 v[4:5], 10, v[4:5]
	v_lshl_add_u64 v[4:5], s[70:71], 0, v[4:5]
	s_lshl_b32 s10, s61, 7
	v_lshl_add_u64 v[4:5], v[4:5], 0, s[10:11]
	v_lshlrev_b32_e32 v0, 1, v146
	v_lshl_add_u64 v[4:5], v[4:5], 0, v[0:1]
	v_add_co_u32_e32 v4, vcc, 0x3c000000, v4
	s_waitcnt lgkmcnt(0)
	s_nop 0
	v_addc_co_u32_e32 v5, vcc, 0, v5, vcc
	s_barrier
	global_load_dwordx4 v[38:41], v[4:5], off offset:512
	ds_read_b32 v0, v7 offset:27648
	s_ashr_i32 s15, s14, 31
	s_lshl_b64 s[16:17], s[14:15], 14
	s_add_u32 s16, s46, s16
	s_addc_u32 s17, s47, s17
	s_waitcnt vmcnt(0)
	v_lshlrev_b32_e32 v4, 16, v38
	s_waitcnt lgkmcnt(0)
	v_mul_f32_e32 v4, v0, v4
	v_and_b32_e32 v5, 0xffff0000, v38
	v_cvt_pk_bf16_f32 v4, v4, v1
	v_lshlrev_b32_e32 v37, 16, v39
	v_mul_f32_e32 v5, v0, v5
	ds_write_b16 v23, v4 offset:18432
	v_cvt_pk_bf16_f32 v4, v5, v1
	v_and_b32_e32 v38, 0xffff0000, v39
	v_mul_f32_e32 v37, v0, v37
	ds_write_b16 v23, v4 offset:18576
	v_cvt_pk_bf16_f32 v4, v37, v1
	v_lshlrev_b32_e32 v39, 16, v40
	v_mul_f32_e32 v38, v0, v38
	ds_write_b16 v23, v4 offset:18720
	v_cvt_pk_bf16_f32 v4, v38, v1
	v_and_b32_e32 v40, 0xffff0000, v40
	v_lshlrev_b32_e32 v42, 16, v41
	v_and_b32_e32 v41, 0xffff0000, v41
	v_mul_f32_e32 v39, v0, v39
	ds_write_b16 v23, v4 offset:18864
	v_cvt_pk_bf16_f32 v4, v39, v1
	v_mul_f32_e32 v40, v0, v40
	v_mul_f32_e32 v42, v0, v42
	v_mul_f32_e32 v0, v0, v41
	ds_write_b16 v23, v4 offset:19008
	v_cvt_pk_bf16_f32 v4, v40, v1
	ds_write_b16 v23, v4 offset:19152
	v_cvt_pk_bf16_f32 v4, v42, v1
	ds_write_b16 v23, v4 offset:19296
	v_cvt_pk_bf16_f32 v0, v0, v1
	ds_write_b16 v23, v0 offset:19440
	s_waitcnt lgkmcnt(0)
	s_barrier
	ds_read_b128 v[38:41], v9
	ds_read_b128 v[42:45], v8 offset:18432
	ds_read_b128 v[46:49], v9 offset:64
	ds_read_b128 v[50:53], v8 offset:18496
	ds_read_b128 v[54:57], v8 offset:20736
	ds_read_b128 v[58:61], v8 offset:20800
	ds_read_b128 v[62:65], v8 offset:23040
	ds_read_b128 v[66:69], v8 offset:23104
	ds_read_b128 v[70:73], v8 offset:25344
	ds_read_b128 v[74:77], v8 offset:25408
	s_waitcnt lgkmcnt(8)
	v_mfma_f32_16x16x32_bf16 v[42:45], v[38:41], v[42:45], 0
	s_waitcnt lgkmcnt(5)
	v_mfma_f32_16x16x32_bf16 v[54:57], v[38:41], v[54:57], 0
	s_waitcnt lgkmcnt(3)
	v_mfma_f32_16x16x32_bf16 v[62:65], v[38:41], v[62:65], 0
	s_waitcnt lgkmcnt(1)
	v_mfma_f32_16x16x32_bf16 v[38:41], v[38:41], v[70:73], 0
	v_mfma_f32_16x16x32_bf16 v[42:45], v[46:49], v[50:53], v[42:45]
	v_mfma_f32_16x16x32_bf16 v[50:53], v[46:49], v[58:61], v[54:57]
	v_mfma_f32_16x16x32_bf16 v[54:57], v[46:49], v[66:69], v[62:65]
	s_nop 5
	v_bfe_u32 v0, v42, 16, 1
	v_bfe_u32 v4, v43, 16, 1
	v_bfe_u32 v5, v44, 16, 1
	s_waitcnt lgkmcnt(0)
	v_mfma_f32_16x16x32_bf16 v[38:41], v[46:49], v[74:77], v[38:41]
	v_bfe_u32 v37, v45, 16, 1
	v_bfe_u32 v46, v50, 16, 1
	v_bfe_u32 v47, v51, 16, 1
	v_bfe_u32 v48, v52, 16, 1
	v_bfe_u32 v49, v53, 16, 1
	v_bfe_u32 v58, v54, 16, 1
	v_bfe_u32 v59, v55, 16, 1
	v_bfe_u32 v60, v56, 16, 1
	v_bfe_u32 v61, v57, 16, 1
	v_bfe_u32 v62, v38, 16, 1
	v_bfe_u32 v63, v39, 16, 1
	v_bfe_u32 v64, v40, 16, 1
	v_add3_u32 v0, v42, v0, s43
	v_add3_u32 v4, v43, v4, s43
	v_add3_u32 v5, v44, v5, s43
	v_add3_u32 v37, v45, v37, s43
	v_add3_u32 v42, v50, v46, s43
	v_add3_u32 v43, v51, v47, s43
	v_add3_u32 v44, v52, v48, s43
	v_add3_u32 v45, v53, v49, s43
	v_add3_u32 v46, v54, v58, s43
	v_add3_u32 v47, v55, v59, s43
	v_add3_u32 v48, v56, v60, s43
	v_add3_u32 v49, v57, v61, s43
	v_add3_u32 v38, v38, v62, s43
	v_add3_u32 v39, v39, v63, s43
	ds_write_b16_d16_hi v24, v0 offset:32768
	ds_write_b16_d16_hi v24, v4 offset:32896
	ds_write_b16_d16_hi v24, v5 offset:33024
	ds_write_b16_d16_hi v24, v37 offset:33152
	ds_write_b16_d16_hi v24, v42 offset:32800
	ds_write_b16_d16_hi v24, v43 offset:32928
	ds_write_b16_d16_hi v24, v44 offset:33056
	ds_write_b16_d16_hi v24, v45 offset:33184
	ds_write_b16_d16_hi v24, v46 offset:32832
	ds_write_b16_d16_hi v24, v47 offset:32960
	ds_write_b16_d16_hi v24, v48 offset:33088
	ds_write_b16_d16_hi v24, v49 offset:33216
	ds_write_b16_d16_hi v24, v38 offset:32864
	ds_write_b16_d16_hi v24, v39 offset:32992
	v_add3_u32 v0, v40, v64, s43
	ds_write_b16_d16_hi v24, v0 offset:33120
	v_bfe_u32 v0, v41, 16, 1
	v_add3_u32 v0, v41, v0, s43
	ds_write_b16_d16_hi v24, v0 offset:33248
	v_and_b32_e32 v90, 63, v156
	v_lshrrev_b32_e32 v91, 6, v156
	v_lshlrev_b32_e32 v90, 4, v90
	v_lshl_add_u32 v90, v91, 11, v90
	ds_read_b128 v[92:95], v90 offset:32768
	ds_read_b128 v[96:99], v90 offset:33792
	s_waitcnt lgkmcnt(0)
	global_store_dwordx4 v90, v[92:95], s[16:17]
	global_store_dwordx4 v90, v[96:99], s[16:17] offset:1024
	s_and_saveexec_b64 s[16:17], s[4:5]
	s_cbranch_execz .LBB0_655
; __device__ __forceinline__ float bf1(bf16_t u) { return __uint_as_float(((unsigned)u) << 16); }
; __device__ __forceinline__ void phase_mlstm_a(const Args& a, unsigned char* lds) {
;     ...
;         if (tid < 64) { float s = 0.f; for (int k = 0; k < 64; ++k) s += bf1(KT[tid * 72 + k]); DN[item * 64 + tid] = s; }
	ds_read_b128 v[38:41], v10 offset:18432
	ds_read_b128 v[42:45], v10 offset:18448
	ds_read_b128 v[46:49], v10 offset:18464
	ds_read_b128 v[50:53], v10 offset:18480
	s_waitcnt lgkmcnt(3)
	v_lshlrev_b32_e32 v0, 16, v38
	v_and_b32_e32 v4, 0xffff0000, v38
	v_add_f32_e32 v0, 0, v0
	v_add_f32_e32 v0, v0, v4
	v_lshlrev_b32_e32 v4, 16, v39
	v_add_f32_e32 v0, v0, v4
	v_and_b32_e32 v4, 0xffff0000, v39
	v_add_f32_e32 v0, v0, v4
	v_lshlrev_b32_e32 v4, 16, v40
	v_add_f32_e32 v0, v0, v4
	v_and_b32_e32 v4, 0xffff0000, v40
	v_add_f32_e32 v0, v0, v4
	v_lshlrev_b32_e32 v4, 16, v41
	v_add_f32_e32 v0, v0, v4
	v_and_b32_e32 v4, 0xffff0000, v41
	v_add_f32_e32 v0, v0, v4
	s_waitcnt lgkmcnt(2)
	v_lshlrev_b32_e32 v4, 16, v42
	v_add_f32_e32 v0, v0, v4
	v_and_b32_e32 v4, 0xffff0000, v42
	v_add_f32_e32 v0, v0, v4
	v_lshlrev_b32_e32 v4, 16, v43
	v_add_f32_e32 v0, v0, v4
	v_and_b32_e32 v4, 0xffff0000, v43
	v_add_f32_e32 v0, v0, v4
	v_lshlrev_b32_e32 v4, 16, v44
	v_add_f32_e32 v0, v0, v4
	v_and_b32_e32 v4, 0xffff0000, v44
	v_add_f32_e32 v0, v0, v4
	v_lshlrev_b32_e32 v4, 16, v45
	v_add_f32_e32 v0, v0, v4
	v_and_b32_e32 v4, 0xffff0000, v45
	v_add_f32_e32 v0, v0, v4
	s_waitcnt lgkmcnt(1)
	v_lshlrev_b32_e32 v4, 16, v46
	v_add_f32_e32 v0, v0, v4
	v_and_b32_e32 v4, 0xffff0000, v46
	v_add_f32_e32 v0, v0, v4
	v_lshlrev_b32_e32 v4, 16, v47
	v_add_f32_e32 v0, v0, v4
	v_and_b32_e32 v4, 0xffff0000, v47
	v_add_f32_e32 v0, v0, v4
	v_lshlrev_b32_e32 v4, 16, v48
	v_add_f32_e32 v0, v0, v4
	v_and_b32_e32 v4, 0xffff0000, v48
	v_add_f32_e32 v0, v0, v4
	v_lshlrev_b32_e32 v4, 16, v49
	v_add_f32_e32 v0, v0, v4
	v_and_b32_e32 v4, 0xffff0000, v49
	v_add_f32_e32 v0, v0, v4
	s_waitcnt lgkmcnt(0)
	v_lshlrev_b32_e32 v4, 16, v50
	v_add_f32_e32 v0, v0, v4
	v_and_b32_e32 v4, 0xffff0000, v50
	v_add_f32_e32 v0, v0, v4
	v_lshlrev_b32_e32 v4, 16, v51
	v_add_f32_e32 v0, v0, v4
	v_and_b32_e32 v4, 0xffff0000, v51
	ds_read_b128 v[38:41], v10 offset:18496
	ds_read_b128 v[42:45], v10 offset:18512
	v_add_f32_e32 v0, v0, v4
	v_lshlrev_b32_e32 v4, 16, v52
	v_add_f32_e32 v0, v0, v4
	v_and_b32_e32 v4, 0xffff0000, v52
	v_add_f32_e32 v0, v0, v4
	v_lshlrev_b32_e32 v4, 16, v53
	v_add_f32_e32 v0, v0, v4
	v_and_b32_e32 v4, 0xffff0000, v53
	v_add_f32_e32 v0, v0, v4
	s_waitcnt lgkmcnt(1)
	v_lshlrev_b32_e32 v4, 16, v38
	v_add_f32_e32 v0, v0, v4
	v_and_b32_e32 v4, 0xffff0000, v38
	v_add_f32_e32 v0, v0, v4
	v_lshlrev_b32_e32 v4, 16, v39
	v_add_f32_e32 v0, v0, v4
	v_and_b32_e32 v4, 0xffff0000, v39
	v_add_f32_e32 v0, v0, v4
	v_lshlrev_b32_e32 v4, 16, v40
	v_add_f32_e32 v0, v0, v4
	v_and_b32_e32 v4, 0xffff0000, v40
	v_add_f32_e32 v0, v0, v4
	v_lshlrev_b32_e32 v4, 16, v41
	v_add_f32_e32 v0, v0, v4
	v_and_b32_e32 v4, 0xffff0000, v41
	v_add_f32_e32 v0, v0, v4
	s_waitcnt lgkmcnt(0)
	v_lshlrev_b32_e32 v4, 16, v42
	v_add_f32_e32 v0, v0, v4
	v_and_b32_e32 v4, 0xffff0000, v42
	v_add_f32_e32 v0, v0, v4
	v_lshlrev_b32_e32 v4, 16, v43
	v_add_f32_e32 v0, v0, v4
	v_and_b32_e32 v4, 0xffff0000, v43
	ds_read_b128 v[38:41], v10 offset:18528
	v_add_f32_e32 v0, v0, v4
	v_lshlrev_b32_e32 v4, 16, v44
	v_add_f32_e32 v0, v0, v4
	v_and_b32_e32 v4, 0xffff0000, v44
	v_add_f32_e32 v0, v0, v4
	v_lshlrev_b32_e32 v4, 16, v45
	v_add_f32_e32 v0, v0, v4
	v_and_b32_e32 v4, 0xffff0000, v45
	v_add_f32_e32 v0, v0, v4
	ds_read_b128 v[42:45], v10 offset:18544
	s_waitcnt lgkmcnt(1)
	v_lshlrev_b32_e32 v4, 16, v38
	v_add_f32_e32 v0, v0, v4
	v_and_b32_e32 v4, 0xffff0000, v38
	v_add_f32_e32 v0, v0, v4
	v_lshlrev_b32_e32 v4, 16, v39
	v_add_f32_e32 v0, v0, v4
	v_and_b32_e32 v4, 0xffff0000, v39
	v_add_f32_e32 v0, v0, v4
	v_lshlrev_b32_e32 v4, 16, v40
	v_add_f32_e32 v0, v0, v4
	v_and_b32_e32 v4, 0xffff0000, v40
	v_add_f32_e32 v0, v0, v4
	v_lshlrev_b32_e32 v4, 16, v41
	v_add_f32_e32 v0, v0, v4
	v_and_b32_e32 v4, 0xffff0000, v41
	v_add_f32_e32 v0, v0, v4
	s_waitcnt lgkmcnt(0)
	v_lshlrev_b32_e32 v4, 16, v42
	v_add_f32_e32 v0, v0, v4
	v_and_b32_e32 v4, 0xffff0000, v42
	v_add_f32_e32 v0, v0, v4
	v_lshlrev_b32_e32 v4, 16, v43
	v_add_f32_e32 v0, v0, v4
	v_and_b32_e32 v4, 0xffff0000, v43
	v_add_f32_e32 v0, v0, v4
	v_lshlrev_b32_e32 v4, 16, v44
	v_add_f32_e32 v0, v0, v4
	v_and_b32_e32 v4, 0xffff0000, v44
	v_add_f32_e32 v0, v0, v4
	v_lshlrev_b32_e32 v4, 16, v45
	v_add_f32_e32 v0, v0, v4
	v_and_b32_e32 v4, 0xffff0000, v45
	v_add_f32_e32 v0, v0, v4
	v_or_b32_e32 v4, s60, v156
	v_ashrrev_i32_e32 v5, 31, v4
	v_lshl_add_u64 v[4:5], v[4:5], 2, s[36:37]
	global_store_dword v[4:5], v0, off
	s_branch .LBB0_655
